# opt28 + sample-loop softmax probabilities rounded to bf16 by v_cvt_pk_bf16_f32 (2 cvt + lo/hi 16-bit LDS stores) instead of bfe/add3 per element
# baseline (speedup 1.0000x reference)
.LBB0_1610:
	s_nop 0
	ds_read_b128 v[16:19], v215
	ds_read_b128 v[20:23], v216
	ds_read_b128 v[24:27], v215 offset:64
	ds_read_b128 v[28:31], v216 offset:64
	ds_read_b128 v[190:193], v215 offset:512
	s_add_i32 s43, s42, 1
	s_waitcnt lgkmcnt(5)
	v_add_f32_e32 v246, v250, v249
	v_add_f32_e32 v247, v251, v248
	v_cndmask_b32_e64 v246, v247, v246, s[6:7]
	v_fmamk_f32 v246, v246, 0x3c2aaaab, v209
	v_mul_f32_e32 v249, 0x4f800000, v246
	v_cmp_gt_f32_e32 vcc, s37, v246
	s_waitcnt lgkmcnt(3)
	v_mfma_f32_16x16x32_bf16 v[16:19], v[16:19], v[20:23], 0
	ds_read_b128 v[20:23], v215 offset:128
	ds_read_b128 v[230:233], v216 offset:128
	s_cmp_ge_u32 s43, s39
	s_nop 1
	v_cndmask_b32_e32 v246, v246, v249, vcc
	v_sqrt_f32_e32 v249, v246
	s_nop 0
	v_add_u32_e32 v250, -1, v249
	v_fma_f32 v252, -v250, v249, v246
	v_add_u32_e32 v251, 1, v249
	s_waitcnt lgkmcnt(3)
	v_mfma_f32_16x16x32_bf16 v[16:19], v[24:27], v[28:31], v[16:19]
	ds_read_b128 v[24:27], v215 offset:192
	ds_read_b128 v[28:31], v216 offset:192
	v_cmp_ge_f32_e64 s[10:11], 0, v252
	s_nop 1
	v_cndmask_b32_e64 v250, v249, v250, s[10:11]
	v_fma_f32 v249, -v251, v249, v246
	v_cmp_lt_f32_e64 s[10:11], 0, v249
	s_nop 1
	v_cndmask_b32_e64 v249, v250, v251, s[10:11]
	s_waitcnt lgkmcnt(2)
	v_mfma_f32_16x16x32_bf16 v[16:19], v[20:23], v[230:233], v[16:19]
	ds_read_b128 v[20:23], v215 offset:256
	ds_read_b128 v[230:233], v216 offset:256
	v_mul_f32_e32 v250, 0x37800000, v249
	v_cndmask_b32_e32 v249, v249, v250, vcc
	v_cmp_class_f32_e32 vcc, v246, v210
	s_nop 1
	v_cndmask_b32_e32 v246, v249, v246, vcc
	v_div_scale_f32 v249, s[10:11], v246, v246, 1.0
	v_rcp_f32_e32 v250, v249
	s_waitcnt lgkmcnt(2)
	v_mfma_f32_16x16x32_bf16 v[16:19], v[24:27], v[28:31], v[16:19]
	ds_read_b128 v[24:27], v215 offset:320
	ds_read_b128 v[28:31], v216 offset:320
	s_nop 0
	v_fma_f32 v248, -v249, v250, 1.0
	v_fmac_f32_e32 v250, v248, v250
	v_div_scale_f32 v248, vcc, 1.0, v246, 1.0
	v_mul_f32_e32 v251, v248, v250
	v_fma_f32 v253, -v249, v251, v248
	v_fmac_f32_e32 v251, v253, v250
	s_waitcnt lgkmcnt(2)
	v_mfma_f32_16x16x32_bf16 v[16:19], v[20:23], v[230:233], v[16:19]
	ds_read_b128 v[20:23], v215 offset:384
	ds_read_b128 v[230:233], v216 offset:384
	v_fma_f32 v248, -v249, v251, v248
	s_nop 0
	v_div_fmas_f32 v248, v248, v250, v251
	v_div_fixup_f32 v246, v248, v246, 1.0
	s_waitcnt lgkmcnt(2)
	v_mfma_f32_16x16x32_bf16 v[16:19], v[24:27], v[28:31], v[16:19]
	ds_read_b128 v[24:27], v215 offset:448
	ds_read_b128 v[28:31], v216 offset:448
	ds_read_b128 v[234:237], v216 offset:512
	ds_write_b32 v203, v246
	s_waitcnt lgkmcnt(0)
	s_barrier
	v_mfma_f32_16x16x32_bf16 v[16:19], v[20:23], v[230:233], v[16:19]
	ds_read_b32 v20, v217
	v_mfma_f32_16x16x32_bf16 v[16:19], v[24:27], v[28:31], v[16:19]
	v_mfma_f32_16x16x32_bf16 v[16:19], v[190:193], v[234:237], v[16:19]
	ds_read_b128 v[246:249], v211
	ds_read_b128 v[250:253], v211 offset:16
	ds_read_b128 v[24:27], v211 offset:64
	ds_read_b128 v[28:31], v211 offset:80
	s_waitcnt lgkmcnt(4)
	s_nop 6
	v_fma_f32 v16, v16, v20, -v177
	v_fma_f32 v17, v17, v20, -v177
	v_fma_f32 v18, v18, v20, -v177
	v_fma_f32 v19, v19, v20, -v177
	v_exp_f32_e32 v192, v16
	v_exp_f32_e32 v193, v17
	v_exp_f32_e32 v190, v18
	v_exp_f32_e32 v191, v19
	v_cvt_pk_bf16_f32 v16, v192, v193
	v_cvt_pk_bf16_f32 v17, v190, v191
	ds_write_b16 v218, v16
	ds_write_b16_d16_hi v218, v16 offset:144
	ds_write_b16 v218, v17 offset:288
	ds_write_b16_d16_hi v218, v17 offset:432
	s_cbranch_scc1 .LBB0_1613
	s_waitcnt lgkmcnt(6)
	v_mfma_scale_f32_32x32x64_f8f6f4 v[230:245], v[32:39], v[246:253], 0, v208, v208 op_sel_hi:[0,0,0]
	v_cvt_pk_bf16_f32 v16, v96, v97
	v_cvt_pk_bf16_f32 v17, v98, v99
	ds_write_b64 v201, v[16:17] offset:37888
	v_cvt_pk_bf16_f32 v18, v100, v101
	v_cvt_pk_bf16_f32 v19, v102, v103
	ds_write_b64 v201, v[18:19] offset:42624
	v_cvt_pk_bf16_f32 v20, v104, v105
	v_cvt_pk_bf16_f32 v21, v106, v107
	ds_write_b64 v201, v[20:21] offset:47360
	v_cvt_pk_bf16_f32 v22, v108, v109
	v_cvt_pk_bf16_f32 v23, v110, v111
	ds_write_b64 v201, v[22:23] offset:52096
	ds_read_b128 v[246:249], v211 offset:128
	ds_read_b128 v[250:253], v211 offset:144
	s_waitcnt lgkmcnt(10)
	v_mfma_scale_f32_32x32x64_f8f6f4 v[230:245], v[40:47], v[24:31], v[230:245], v208, v208 op_sel_hi:[0,0,0]
	v_cvt_pk_bf16_f32 v16, v112, v113
	v_cvt_pk_bf16_f32 v17, v114, v115
	ds_write_b64 v201, v[16:17] offset:56832
	v_cvt_pk_bf16_f32 v18, v116, v117
	v_cvt_pk_bf16_f32 v19, v118, v119
	ds_write_b64 v201, v[18:19] offset:61568
	v_cvt_pk_bf16_f32 v20, v120, v121
	v_cvt_pk_bf16_f32 v21, v122, v123
	ds_write_b64 v204, v[20:21] offset:28416
	v_cvt_pk_bf16_f32 v22, v124, v125
	v_cvt_pk_bf16_f32 v23, v126, v127
	ds_write_b64 v204, v[22:23] offset:33152
	v_mul_f32_e32 v18, v128, v128
	v_fmac_f32_e32 v18, v129, v129
	v_fmac_f32_e32 v18, v130, v130
	v_fmac_f32_e32 v18, v131, v131
	v_cvt_pk_bf16_f32 v16, v128, v129
	v_cvt_pk_bf16_f32 v17, v130, v131
	v_add_f32_dpp v18, v18, v18 quad_perm:[1,0,3,2] row_mask:0xf bank_mask:0xf
	ds_write_b64 v213, v[16:17] offset:38400
	s_nop 0
	v_add_f32_dpp v18, v18, v18 quad_perm:[2,3,0,1] row_mask:0xf bank_mask:0xf
	s_nop 1
	v_add_f32_dpp v18, v18, v18 row_half_mirror row_mask:0xf bank_mask:0xf
	v_mul_f32_e32 v18, 0.5, v18
	ds_write_b32 v202, v18 offset:2048
	ds_read_b128 v[24:27], v211 offset:192
	ds_read_b128 v[28:31], v211 offset:208
	s_waitcnt lgkmcnt(8)
	v_mfma_scale_f32_32x32x64_f8f6f4 v[230:245], v[48:55], v[246:253], v[230:245], v208, v208 op_sel_hi:[0,0,0]
	v_readlane_b32 s0, v227, s41
	s_ashr_i32 s1, s0, 31
	s_lshl_b64 s[0:1], s[0:1], 7
	s_or_b32 s0, s0, 64
	s_lshl_b64 s[2:3], s[0:1], 10
	v_lshl_add_u64 v[16:17], v[182:183], 0, s[2:3]
	v_add_co_u32_e32 v18, vcc, 0x2000, v16
	s_lshl_b64 s[0:1], s[0:1], 7
	s_nop 0
	v_addc_co_u32_e32 v19, vcc, 0, v17, vcc
	global_load_dwordx4 v[96:99], v[16:17], off nt
	global_load_dwordx4 v[100:103], v[18:19], off nt
	v_add_co_u32_e32 v18, vcc, 0x4000, v16
	s_nop 1
	v_addc_co_u32_e32 v19, vcc, 0, v17, vcc
	v_add_co_u32_e32 v20, vcc, 0x6000, v16
	s_nop 1
	v_addc_co_u32_e32 v21, vcc, 0, v17, vcc
	global_load_dwordx4 v[104:107], v[18:19], off nt
	ds_read_b128 v[246:249], v211
	ds_read_b128 v[250:253], v211 offset:16
	s_waitcnt lgkmcnt(2)
	v_mfma_scale_f32_32x32x64_f8f6f4 v[230:245], v[56:63], v[24:31], v[230:245], v208, v208 op_sel_hi:[0,0,0]
	global_load_dwordx4 v[108:111], v[20:21], off nt
	v_add_co_u32_e32 v18, vcc, 0x8000, v16
	s_nop 1
	v_addc_co_u32_e32 v19, vcc, 0, v17, vcc
	v_add_co_u32_e32 v20, vcc, 0xa000, v16
	s_nop 1
	v_addc_co_u32_e32 v21, vcc, 0, v17, vcc
	global_load_dwordx4 v[112:115], v[18:19], off nt
	global_load_dwordx4 v[116:119], v[20:21], off nt
	v_add_co_u32_e32 v18, vcc, 0xc000, v16
	s_nop 1
	v_addc_co_u32_e32 v19, vcc, 0, v17, vcc
	v_add_co_u32_e32 v16, vcc, 0xe000, v16
	s_nop 1
	v_addc_co_u32_e32 v17, vcc, 0, v17, vcc
	global_load_dwordx4 v[120:123], v[18:19], off nt
	global_load_dwordx4 v[124:127], v[16:17], off nt
	v_lshl_add_u64 v[16:17], v[184:185], 0, s[0:1]
	global_load_dwordx4 v[128:131], v[16:17], off nt
	ds_read_b128 v[24:27], v211 offset:64
	ds_read_b128 v[28:31], v211 offset:80
	v_mul_f32_e32 v180, v231, v231
	v_fmac_f32_e32 v180, v230, v230
	v_fmac_f32_e32 v180, v232, v232
	v_fmac_f32_e32 v180, v233, v233
	v_fmac_f32_e32 v180, v234, v234
	v_fmac_f32_e32 v180, v235, v235
	v_fmac_f32_e32 v180, v236, v236
	v_fmac_f32_e32 v180, v237, v237
	v_fmac_f32_e32 v180, v238, v238
	v_fmac_f32_e32 v180, v239, v239
	v_fmac_f32_e32 v180, v240, v240
	v_fmac_f32_e32 v180, v241, v241
	v_fmac_f32_e32 v180, v242, v242
	v_fmac_f32_e32 v180, v243, v243
	v_fmac_f32_e32 v180, v244, v244
	v_fmac_f32_e32 v180, v245, v245
	s_waitcnt lgkmcnt(2)
	v_mfma_scale_f32_32x32x64_f8f6f4 v[230:245], v[64:71], v[246:253], 0, v208, v208 op_sel_hi:[0,0,0]
	ds_read_b128 v[246:249], v211 offset:128
	ds_read_b128 v[250:253], v211 offset:144
	s_waitcnt lgkmcnt(2)
	v_mfma_scale_f32_32x32x64_f8f6f4 v[230:245], v[72:79], v[24:31], v[230:245], v208, v208 op_sel_hi:[0,0,0]
	ds_read_b128 v[24:27], v211 offset:192
	ds_read_b128 v[28:31], v211 offset:208
	s_waitcnt lgkmcnt(2)
	v_mfma_scale_f32_32x32x64_f8f6f4 v[230:245], v[80:87], v[246:253], v[230:245], v208, v208 op_sel_hi:[0,0,0]
	ds_read_b128 v[246:249], v211 offset:8704
	ds_read_b128 v[250:253], v211 offset:8720
	s_waitcnt lgkmcnt(2)
	v_mfma_scale_f32_32x32x64_f8f6f4 v[230:245], v[88:95], v[24:31], v[230:245], v208, v208 op_sel_hi:[0,0,0]
	ds_read_b128 v[24:27], v211 offset:8768
	ds_read_b128 v[28:31], v211 offset:8784
	s_nop 15
	s_nop 1
	v_fmac_f32_e32 v180, v230, v230
	v_fmac_f32_e32 v180, v231, v231
	v_fmac_f32_e32 v180, v232, v232
	v_fmac_f32_e32 v180, v233, v233
	v_fmac_f32_e32 v180, v234, v234
	v_fmac_f32_e32 v180, v235, v235
	v_fmac_f32_e32 v180, v236, v236
	v_fmac_f32_e32 v180, v237, v237
	v_fmac_f32_e32 v180, v238, v238
	v_fmac_f32_e32 v180, v239, v239
	v_fmac_f32_e32 v180, v240, v240
	v_fmac_f32_e32 v180, v241, v241
	v_fmac_f32_e32 v180, v242, v242
	v_fmac_f32_e32 v180, v243, v243
	v_fmac_f32_e32 v180, v244, v244
	v_fmac_f32_e32 v180, v245, v245
	s_waitcnt lgkmcnt(2)
	v_mfma_scale_f32_32x32x64_f8f6f4 v[230:245], v[32:39], v[246:253], 0, v208, v208 op_sel_hi:[0,0,0]
	ds_read_b128 v[246:249], v211 offset:8832
	ds_read_b128 v[250:253], v211 offset:8848
	s_waitcnt lgkmcnt(2)
	v_mfma_scale_f32_32x32x64_f8f6f4 v[230:245], v[40:47], v[24:31], v[230:245], v208, v208 op_sel_hi:[0,0,0]
	ds_read_b128 v[24:27], v211 offset:8896
	ds_read_b128 v[28:31], v211 offset:8912
	s_waitcnt lgkmcnt(2)
	v_mfma_scale_f32_32x32x64_f8f6f4 v[230:245], v[48:55], v[246:253], v[230:245], v208, v208 op_sel_hi:[0,0,0]
	ds_read_b128 v[246:249], v211 offset:8704
	ds_read_b128 v[250:253], v211 offset:8720
	s_waitcnt lgkmcnt(2)
	v_mfma_scale_f32_32x32x64_f8f6f4 v[230:245], v[56:63], v[24:31], v[230:245], v208, v208 op_sel_hi:[0,0,0]
	ds_read_b128 v[24:27], v211 offset:8768
	ds_read_b128 v[28:31], v211 offset:8784
	s_nop 15
	s_nop 1
	v_mul_f32_e32 v229, v231, v231
	v_fmac_f32_e32 v229, v230, v230
	v_fmac_f32_e32 v229, v232, v232
	v_fmac_f32_e32 v229, v233, v233
	v_fmac_f32_e32 v229, v234, v234
	v_fmac_f32_e32 v229, v235, v235
	v_fmac_f32_e32 v229, v236, v236
	v_fmac_f32_e32 v229, v237, v237
	v_fmac_f32_e32 v229, v238, v238
	v_fmac_f32_e32 v229, v239, v239
	v_fmac_f32_e32 v229, v240, v240
	v_fmac_f32_e32 v229, v241, v241
	v_fmac_f32_e32 v229, v242, v242
	v_fmac_f32_e32 v229, v243, v243
	v_fmac_f32_e32 v229, v244, v244
	v_fmac_f32_e32 v229, v245, v245
	s_waitcnt lgkmcnt(2)
	v_mfma_scale_f32_32x32x64_f8f6f4 v[230:245], v[64:71], v[246:253], 0, v208, v208 op_sel_hi:[0,0,0]
	ds_read_b128 v[246:249], v211 offset:8832
	ds_read_b128 v[250:253], v211 offset:8848
	s_waitcnt lgkmcnt(2)
	v_mfma_scale_f32_32x32x64_f8f6f4 v[230:245], v[72:79], v[24:31], v[230:245], v208, v208 op_sel_hi:[0,0,0]
	ds_read_b128 v[24:27], v211 offset:8896
	ds_read_b128 v[28:31], v211 offset:8912
	s_waitcnt lgkmcnt(2)
	v_mfma_scale_f32_32x32x64_f8f6f4 v[230:245], v[80:87], v[246:253], v[230:245], v208, v208 op_sel_hi:[0,0,0]
	s_waitcnt lgkmcnt(0)
	v_mfma_scale_f32_32x32x64_f8f6f4 v[230:245], v[88:95], v[24:31], v[230:245], v208, v208 op_sel_hi:[0,0,0]
	s_waitcnt vmcnt(9)
	v_cvt_pk_fp8_f32 v16, v136, v137
	v_cvt_pk_fp8_f32 v17, v148, v149
	v_cvt_pk_fp8_f32 v18, v160, v161
	v_cvt_pk_fp8_f32 v19, v144, v145
	v_cvt_pk_fp8_f32 v20, v156, v157
	v_cvt_pk_fp8_f32 v21, v140, v141
	v_cvt_pk_fp8_f32 v22, v152, v153
	v_cvt_pk_fp8_f32 v23, v164, v165
	v_cvt_pk_fp8_f32 v16, v138, v139 op_sel:[0,0,1]
	v_cvt_pk_fp8_f32 v17, v150, v151 op_sel:[0,0,1]
	v_cvt_pk_fp8_f32 v18, v162, v163 op_sel:[0,0,1]
	v_cvt_pk_fp8_f32 v19, v146, v147 op_sel:[0,0,1]
	v_cvt_pk_fp8_f32 v20, v158, v159 op_sel:[0,0,1]
	v_cvt_pk_fp8_f32 v21, v142, v143 op_sel:[0,0,1]
	v_cvt_pk_fp8_f32 v22, v154, v155 op_sel:[0,0,1]
	v_cvt_pk_fp8_f32 v23, v166, v167 op_sel:[0,0,1]
	s_nop 1
	ds_write_b32 v228, v16
	ds_write_b32 v228, v17 offset:2176
	ds_write_b32 v228, v18 offset:4352
	ds_write_b32 v228, v19 offset:6528
	ds_write_b32 v228, v20 offset:8704
	ds_write_b32 v228, v21 offset:10880
	ds_write_b32 v228, v22 offset:13056
	ds_write_b32 v228, v23 offset:15232
	v_fmac_f32_e32 v229, v230, v230
	v_fmac_f32_e32 v229, v231, v231
	v_fmac_f32_e32 v229, v232, v232
	v_fmac_f32_e32 v229, v233, v233
	v_fmac_f32_e32 v229, v234, v234
	v_fmac_f32_e32 v229, v235, v235
	v_fmac_f32_e32 v229, v236, v236
	v_fmac_f32_e32 v229, v237, v237
	v_fmac_f32_e32 v229, v238, v238
	v_fmac_f32_e32 v229, v239, v239
	v_fmac_f32_e32 v229, v240, v240
	v_fmac_f32_e32 v229, v241, v241
	v_fmac_f32_e32 v229, v242, v242
	v_fmac_f32_e32 v229, v243, v243
	v_fmac_f32_e32 v229, v244, v244
	v_fmac_f32_e32 v229, v245, v245

.LBB0_1615:
	s_nop 0
	ds_read_b128 v[16:19], v215
	ds_read_b128 v[20:23], v216 offset:37888
	ds_read_b128 v[24:27], v215 offset:64
	ds_read_b128 v[28:31], v216 offset:37952
	ds_read_b128 v[230:233], v215 offset:512
	s_add_i32 s44, s42, 2
	s_waitcnt lgkmcnt(5)
	v_add_f32_e32 v246, v250, v249
	v_add_f32_e32 v247, v251, v248
	v_cndmask_b32_e64 v246, v247, v246, s[6:7]
	v_fmamk_f32 v246, v246, 0x3c2aaaab, v209
	v_mul_f32_e32 v249, 0x4f800000, v246
	v_cmp_gt_f32_e32 vcc, s37, v246
	s_waitcnt lgkmcnt(3)
	v_mfma_f32_16x16x32_bf16 v[16:19], v[16:19], v[20:23], 0
	ds_read_b128 v[20:23], v215 offset:128
	ds_read_b128 v[234:237], v216 offset:38016
	s_cmp_ge_u32 s44, s39
	s_cselect_b64 s[0:1], -1, 0
	s_nop 1
	v_cndmask_b32_e32 v246, v246, v249, vcc
	v_sqrt_f32_e32 v249, v246
	s_nop 0
	v_add_u32_e32 v250, -1, v249
	v_fma_f32 v252, -v250, v249, v246
	v_add_u32_e32 v251, 1, v249
	s_waitcnt lgkmcnt(3)
	v_mfma_f32_16x16x32_bf16 v[16:19], v[24:27], v[28:31], v[16:19]
	ds_read_b128 v[24:27], v215 offset:192
	ds_read_b128 v[28:31], v216 offset:38080
	v_cmp_ge_f32_e64 s[10:11], 0, v252
	s_nop 1
	v_cndmask_b32_e64 v250, v249, v250, s[10:11]
	v_fma_f32 v249, -v251, v249, v246
	v_cmp_lt_f32_e64 s[10:11], 0, v249
	s_nop 1
	v_cndmask_b32_e64 v249, v250, v251, s[10:11]
	s_waitcnt lgkmcnt(2)
	v_mfma_f32_16x16x32_bf16 v[16:19], v[20:23], v[234:237], v[16:19]
	ds_read_b128 v[20:23], v215 offset:256
	ds_read_b128 v[234:237], v216 offset:38144
	v_mul_f32_e32 v250, 0x37800000, v249
	v_cndmask_b32_e32 v249, v249, v250, vcc
	v_cmp_class_f32_e32 vcc, v246, v210
	s_nop 1
	v_cndmask_b32_e32 v246, v249, v246, vcc
	v_div_scale_f32 v249, s[10:11], v246, v246, 1.0
	v_rcp_f32_e32 v250, v249
	s_waitcnt lgkmcnt(2)
	v_mfma_f32_16x16x32_bf16 v[16:19], v[24:27], v[28:31], v[16:19]
	ds_read_b128 v[24:27], v215 offset:320
	ds_read_b128 v[28:31], v216 offset:38208
	s_nop 0
	v_fma_f32 v248, -v249, v250, 1.0
	v_fmac_f32_e32 v250, v248, v250
	v_div_scale_f32 v248, vcc, 1.0, v246, 1.0
	v_mul_f32_e32 v251, v248, v250
	v_fma_f32 v253, -v249, v251, v248
	v_fmac_f32_e32 v251, v253, v250
	s_waitcnt lgkmcnt(2)
	v_mfma_f32_16x16x32_bf16 v[16:19], v[20:23], v[234:237], v[16:19]
	ds_read_b128 v[20:23], v215 offset:384
	ds_read_b128 v[234:237], v216 offset:38272
	v_fma_f32 v248, -v249, v251, v248
	s_nop 0
	v_div_fmas_f32 v248, v248, v250, v251
	v_div_fixup_f32 v246, v248, v246, 1.0
	s_waitcnt lgkmcnt(2)
	v_mfma_f32_16x16x32_bf16 v[16:19], v[24:27], v[28:31], v[16:19]
	ds_read_b128 v[24:27], v215 offset:448
	ds_read_b128 v[28:31], v216 offset:38336
	ds_read_b128 v[238:241], v216 offset:38400
	ds_write_b32 v203, v246
	s_and_b64 vcc, exec, s[0:1]
	s_waitcnt lgkmcnt(0)
	s_barrier
	v_mfma_f32_16x16x32_bf16 v[16:19], v[20:23], v[234:237], v[16:19]
	ds_read_b32 v20, v217
	v_mfma_f32_16x16x32_bf16 v[16:19], v[24:27], v[28:31], v[16:19]
	v_mfma_f32_16x16x32_bf16 v[16:19], v[230:233], v[238:241], v[16:19]
	ds_read_b128 v[246:249], v207
	ds_read_b128 v[250:253], v207 offset:16
	ds_read_b128 v[24:27], v207 offset:64
	ds_read_b128 v[28:31], v207 offset:80
	s_waitcnt lgkmcnt(4)
	s_nop 6
	v_fma_f32 v16, v16, v20, -v177
	v_fma_f32 v17, v17, v20, -v177
	v_fma_f32 v18, v18, v20, -v177
	v_fma_f32 v19, v19, v20, -v177
	v_exp_f32_e32 v16, v16
	v_exp_f32_e32 v17, v17
	v_exp_f32_e32 v18, v18
	v_exp_f32_e32 v19, v19
	v_add_f32_e32 v188, v188, v192
	v_add_f32_e32 v189, v189, v193
	v_add_f32_e32 v186, v186, v190
	v_add_f32_e32 v187, v187, v191
	v_add_f32_e32 v188, v188, v16
	v_add_f32_e32 v189, v189, v17
	v_add_f32_e32 v186, v186, v18
	v_add_f32_e32 v187, v187, v19
	v_cvt_pk_bf16_f32 v20, v16, v17
	v_cvt_pk_bf16_f32 v21, v18, v19
	ds_write_b16 v218, v20
	ds_write_b16_d16_hi v218, v20 offset:144
	ds_write_b16 v218, v21 offset:288
	ds_write_b16_d16_hi v218, v21 offset:432
	s_cbranch_vccnz .LBB0_1618
	s_waitcnt lgkmcnt(6)
	v_mfma_scale_f32_32x32x64_f8f6f4 v[230:245], v[32:39], v[246:253], 0, v208, v208 op_sel_hi:[0,0,0]
	v_cvt_pk_bf16_f32 v16, v136, v137
	v_cvt_pk_bf16_f32 v17, v138, v139
	ds_write_b64 v201, v[16:17] offset:0
	v_cvt_pk_bf16_f32 v18, v148, v149
	v_cvt_pk_bf16_f32 v19, v150, v151
	ds_write_b64 v201, v[18:19] offset:4736
	v_cvt_pk_bf16_f32 v20, v160, v161
	v_cvt_pk_bf16_f32 v21, v162, v163
	ds_write_b64 v201, v[20:21] offset:9472
	v_cvt_pk_bf16_f32 v22, v144, v145
	v_cvt_pk_bf16_f32 v23, v146, v147
	ds_write_b64 v201, v[22:23] offset:14208
	ds_read_b128 v[246:249], v207 offset:128
	ds_read_b128 v[250:253], v207 offset:144
	s_waitcnt lgkmcnt(10)
	v_mfma_scale_f32_32x32x64_f8f6f4 v[230:245], v[40:47], v[24:31], v[230:245], v208, v208 op_sel_hi:[0,0,0]
	v_cvt_pk_bf16_f32 v16, v156, v157
	v_cvt_pk_bf16_f32 v17, v158, v159
	ds_write_b64 v201, v[16:17] offset:18944
	v_cvt_pk_bf16_f32 v18, v140, v141
	v_cvt_pk_bf16_f32 v19, v142, v143
	ds_write_b64 v201, v[18:19] offset:23680
	v_cvt_pk_bf16_f32 v20, v152, v153
	v_cvt_pk_bf16_f32 v21, v154, v155
	ds_write_b64 v201, v[20:21] offset:28416
	v_cvt_pk_bf16_f32 v22, v164, v165
	v_cvt_pk_bf16_f32 v23, v166, v167
	ds_write_b64 v201, v[22:23] offset:33152
	v_mul_f32_e32 v18, v132, v132
	v_fmac_f32_e32 v18, v133, v133
	v_fmac_f32_e32 v18, v134, v134
	v_fmac_f32_e32 v18, v135, v135
	v_cvt_pk_bf16_f32 v16, v132, v133
	v_cvt_pk_bf16_f32 v17, v134, v135
	v_add_f32_dpp v18, v18, v18 quad_perm:[1,0,3,2] row_mask:0xf bank_mask:0xf
	ds_write_b64 v213, v[16:17] offset:512
	s_nop 0
	v_add_f32_dpp v18, v18, v18 quad_perm:[2,3,0,1] row_mask:0xf bank_mask:0xf
	s_nop 1
	v_add_f32_dpp v18, v18, v18 row_half_mirror row_mask:0xf bank_mask:0xf
	v_mul_f32_e32 v18, 0.5, v18
	ds_write_b32 v202, v18
	ds_read_b128 v[24:27], v207 offset:192
	ds_read_b128 v[28:31], v207 offset:208
	s_waitcnt lgkmcnt(8)
	v_mfma_scale_f32_32x32x64_f8f6f4 v[230:245], v[48:55], v[246:253], v[230:245], v208, v208 op_sel_hi:[0,0,0]
	s_add_i32 s2, s41, 1
	v_readlane_b32 s2, v227, s2
	s_ashr_i32 s3, s2, 31
	s_lshl_b64 s[10:11], s[2:3], 17
	v_lshl_add_u64 v[16:17], v[182:183], 0, s[10:11]
	v_add_co_u32_e32 v18, vcc, 0x2000, v16
	s_lshl_b64 s[2:3], s[2:3], 14
	s_nop 0
	v_addc_co_u32_e32 v19, vcc, 0, v17, vcc
	global_load_dwordx4 v[136:139], v[16:17], off nt
	global_load_dwordx4 v[148:151], v[18:19], off nt
	v_add_co_u32_e32 v18, vcc, 0x4000, v16
	s_nop 1
	v_addc_co_u32_e32 v19, vcc, 0, v17, vcc
	v_add_co_u32_e32 v20, vcc, 0x6000, v16
	s_nop 1
	v_addc_co_u32_e32 v21, vcc, 0, v17, vcc
	global_load_dwordx4 v[160:163], v[18:19], off nt
	ds_read_b128 v[246:249], v207
	ds_read_b128 v[250:253], v207 offset:16
	s_waitcnt lgkmcnt(2)
	v_mfma_scale_f32_32x32x64_f8f6f4 v[230:245], v[56:63], v[24:31], v[230:245], v208, v208 op_sel_hi:[0,0,0]
	global_load_dwordx4 v[144:147], v[20:21], off nt
	v_add_co_u32_e32 v18, vcc, 0x8000, v16
	s_nop 1
	v_addc_co_u32_e32 v19, vcc, 0, v17, vcc
	v_add_co_u32_e32 v20, vcc, 0xa000, v16
	s_nop 1
	v_addc_co_u32_e32 v21, vcc, 0, v17, vcc
	global_load_dwordx4 v[156:159], v[18:19], off nt
	global_load_dwordx4 v[140:143], v[20:21], off nt
	v_add_co_u32_e32 v18, vcc, 0xc000, v16
	s_nop 1
	v_addc_co_u32_e32 v19, vcc, 0, v17, vcc
	v_add_co_u32_e32 v16, vcc, 0xe000, v16
	s_nop 1
	v_addc_co_u32_e32 v17, vcc, 0, v17, vcc
	global_load_dwordx4 v[152:155], v[18:19], off nt
	global_load_dwordx4 v[164:167], v[16:17], off nt
	v_lshl_add_u64 v[16:17], v[184:185], 0, s[2:3]
	global_load_dwordx4 v[132:135], v[16:17], off nt
	ds_read_b128 v[24:27], v207 offset:64
	ds_read_b128 v[28:31], v207 offset:80
	v_mul_f32_e32 v180, v231, v231
	v_fmac_f32_e32 v180, v230, v230
	v_fmac_f32_e32 v180, v232, v232
	v_fmac_f32_e32 v180, v233, v233
	v_fmac_f32_e32 v180, v234, v234
	v_fmac_f32_e32 v180, v235, v235
	v_fmac_f32_e32 v180, v236, v236
	v_fmac_f32_e32 v180, v237, v237
	v_fmac_f32_e32 v180, v238, v238
	v_fmac_f32_e32 v180, v239, v239
	v_fmac_f32_e32 v180, v240, v240
	v_fmac_f32_e32 v180, v241, v241
	v_fmac_f32_e32 v180, v242, v242
	v_fmac_f32_e32 v180, v243, v243
	v_fmac_f32_e32 v180, v244, v244
	v_fmac_f32_e32 v180, v245, v245
	s_waitcnt lgkmcnt(2)
	v_mfma_scale_f32_32x32x64_f8f6f4 v[230:245], v[64:71], v[246:253], 0, v208, v208 op_sel_hi:[0,0,0]
	ds_read_b128 v[246:249], v207 offset:128
	ds_read_b128 v[250:253], v207 offset:144
	s_waitcnt lgkmcnt(2)
	v_mfma_scale_f32_32x32x64_f8f6f4 v[230:245], v[72:79], v[24:31], v[230:245], v208, v208 op_sel_hi:[0,0,0]
	ds_read_b128 v[24:27], v207 offset:192
	ds_read_b128 v[28:31], v207 offset:208
	s_waitcnt lgkmcnt(2)
	v_mfma_scale_f32_32x32x64_f8f6f4 v[230:245], v[80:87], v[246:253], v[230:245], v208, v208 op_sel_hi:[0,0,0]
	ds_read_b128 v[246:249], v207 offset:8704
	ds_read_b128 v[250:253], v207 offset:8720
	s_waitcnt lgkmcnt(2)
	v_mfma_scale_f32_32x32x64_f8f6f4 v[230:245], v[88:95], v[24:31], v[230:245], v208, v208 op_sel_hi:[0,0,0]
	ds_read_b128 v[24:27], v207 offset:8768
	ds_read_b128 v[28:31], v207 offset:8784
	s_nop 15
	s_nop 1
	v_fmac_f32_e32 v180, v230, v230
	v_fmac_f32_e32 v180, v231, v231
	v_fmac_f32_e32 v180, v232, v232
	v_fmac_f32_e32 v180, v233, v233
	v_fmac_f32_e32 v180, v234, v234
	v_fmac_f32_e32 v180, v235, v235
	v_fmac_f32_e32 v180, v236, v236
	v_fmac_f32_e32 v180, v237, v237
	v_fmac_f32_e32 v180, v238, v238
	v_fmac_f32_e32 v180, v239, v239
	v_fmac_f32_e32 v180, v240, v240
	v_fmac_f32_e32 v180, v241, v241
	v_fmac_f32_e32 v180, v242, v242
	v_fmac_f32_e32 v180, v243, v243
	v_fmac_f32_e32 v180, v244, v244
	v_fmac_f32_e32 v180, v245, v245
	s_waitcnt lgkmcnt(2)
	v_mfma_scale_f32_32x32x64_f8f6f4 v[230:245], v[32:39], v[246:253], 0, v208, v208 op_sel_hi:[0,0,0]
	ds_read_b128 v[246:249], v207 offset:8832
	ds_read_b128 v[250:253], v207 offset:8848
	s_waitcnt lgkmcnt(2)
	v_mfma_scale_f32_32x32x64_f8f6f4 v[230:245], v[40:47], v[24:31], v[230:245], v208, v208 op_sel_hi:[0,0,0]
	ds_read_b128 v[24:27], v207 offset:8896
	ds_read_b128 v[28:31], v207 offset:8912
	s_waitcnt lgkmcnt(2)
	v_mfma_scale_f32_32x32x64_f8f6f4 v[230:245], v[48:55], v[246:253], v[230:245], v208, v208 op_sel_hi:[0,0,0]
	ds_read_b128 v[246:249], v207 offset:8704
	ds_read_b128 v[250:253], v207 offset:8720
	s_waitcnt lgkmcnt(2)
	v_mfma_scale_f32_32x32x64_f8f6f4 v[230:245], v[56:63], v[24:31], v[230:245], v208, v208 op_sel_hi:[0,0,0]
	ds_read_b128 v[24:27], v207 offset:8768
	ds_read_b128 v[28:31], v207 offset:8784
	s_nop 15
	s_nop 1
	v_mul_f32_e32 v229, v231, v231
	v_fmac_f32_e32 v229, v230, v230
	v_fmac_f32_e32 v229, v232, v232
	v_fmac_f32_e32 v229, v233, v233
	v_fmac_f32_e32 v229, v234, v234
	v_fmac_f32_e32 v229, v235, v235
	v_fmac_f32_e32 v229, v236, v236
	v_fmac_f32_e32 v229, v237, v237
	v_fmac_f32_e32 v229, v238, v238
	v_fmac_f32_e32 v229, v239, v239
	v_fmac_f32_e32 v229, v240, v240
	v_fmac_f32_e32 v229, v241, v241
	v_fmac_f32_e32 v229, v242, v242
	v_fmac_f32_e32 v229, v243, v243
	v_fmac_f32_e32 v229, v244, v244
	v_fmac_f32_e32 v229, v245, v245
	s_waitcnt lgkmcnt(2)
	v_mfma_scale_f32_32x32x64_f8f6f4 v[230:245], v[64:71], v[246:253], 0, v208, v208 op_sel_hi:[0,0,0]
	ds_read_b128 v[246:249], v207 offset:8832
	ds_read_b128 v[250:253], v207 offset:8848
	s_waitcnt lgkmcnt(2)
	v_mfma_scale_f32_32x32x64_f8f6f4 v[230:245], v[72:79], v[24:31], v[230:245], v208, v208 op_sel_hi:[0,0,0]
	ds_read_b128 v[24:27], v207 offset:8896
	ds_read_b128 v[28:31], v207 offset:8912
	s_waitcnt lgkmcnt(2)
	v_mfma_scale_f32_32x32x64_f8f6f4 v[230:245], v[80:87], v[246:253], v[230:245], v208, v208 op_sel_hi:[0,0,0]
	s_waitcnt lgkmcnt(0)
	v_mfma_scale_f32_32x32x64_f8f6f4 v[230:245], v[88:95], v[24:31], v[230:245], v208, v208 op_sel_hi:[0,0,0]
	s_waitcnt vmcnt(9)
	v_cvt_pk_fp8_f32 v16, v96, v97
	v_cvt_pk_fp8_f32 v17, v100, v101
	v_cvt_pk_fp8_f32 v18, v104, v105
	v_cvt_pk_fp8_f32 v19, v108, v109
	v_cvt_pk_fp8_f32 v20, v112, v113
	v_cvt_pk_fp8_f32 v21, v116, v117
	v_cvt_pk_fp8_f32 v22, v120, v121
	v_cvt_pk_fp8_f32 v23, v124, v125
	v_cvt_pk_fp8_f32 v16, v98, v99 op_sel:[0,0,1]
	v_cvt_pk_fp8_f32 v17, v102, v103 op_sel:[0,0,1]
	v_cvt_pk_fp8_f32 v18, v106, v107 op_sel:[0,0,1]
	v_cvt_pk_fp8_f32 v19, v110, v111 op_sel:[0,0,1]
	v_cvt_pk_fp8_f32 v20, v114, v115 op_sel:[0,0,1]
	v_cvt_pk_fp8_f32 v21, v118, v119 op_sel:[0,0,1]
	v_cvt_pk_fp8_f32 v22, v122, v123 op_sel:[0,0,1]
	v_cvt_pk_fp8_f32 v23, v126, v127 op_sel:[0,0,1]
	s_nop 1
	ds_write_b32 v228, v16 offset:17408
	ds_write_b32 v228, v17 offset:19584
	ds_write_b32 v228, v18 offset:21760
	ds_write_b32 v228, v19 offset:23936
	ds_write_b32 v228, v20 offset:26112
	ds_write_b32 v228, v21 offset:28288
	ds_write_b32 v228, v22 offset:30464
	ds_write_b32 v228, v23 offset:32640
	v_fmac_f32_e32 v229, v230, v230
	v_fmac_f32_e32 v229, v231, v231
	v_fmac_f32_e32 v229, v232, v232
	v_fmac_f32_e32 v229, v233, v233
	v_fmac_f32_e32 v229, v234, v234
	v_fmac_f32_e32 v229, v235, v235
	v_fmac_f32_e32 v229, v236, v236
	v_fmac_f32_e32 v229, v237, v237
	v_fmac_f32_e32 v229, v238, v238
	v_fmac_f32_e32 v229, v239, v239
	v_fmac_f32_e32 v229, v240, v240
	v_fmac_f32_e32 v229, v241, v241
	v_fmac_f32_e32 v229, v242, v242
	v_fmac_f32_e32 v229, v243, v243
	v_fmac_f32_e32 v229, v244, v244
	v_fmac_f32_e32 v229, v245, v245
